# proj GEMM K-loop: per-phase s_setprio flips deleted, static s_setprio 1 for waves 4-7 (A/B of lever 4)
# speedup vs baseline: 1.0096x; 1.0096x over previous
; DI int opaque_tid() { int t = threadIdx.x; asm volatile("" : "+v"(t)); return t; }
; #define PG8_STAGE(bufoff, gbase, voff) do { _Pragma("unroll") for (int _i = 0; _i < 2; ++_i) \
;         __builtin_amdgcn_global_load_lds((const unsigned*)((const char*)(gbase) + (voff)[_i]), (LAS unsigned*)(lds + (bufoff) + ldsw + _i * 8192), 16, 0, 0); } while (0)
; #define PG8_WAIT_V(n) asm volatile("s_waitcnt vmcnt(" #n ")" ::: "memory")
; #define PG8_BAR __builtin_amdgcn_s_barrier()
; template <class Epi>
; DI void gemm_phase(LAS unsigned char* lds, const Gemm g, const StaticOrder& S, const Epi& E) {
;     const int tid = opaque_tid(), wid = __builtin_amdgcn_readfirstlane(tid >> 6), lane = tid & 63, wr = wid >> 2, wc = wid & 3, fr = lane & 15, fq = lane >> 4;
;     const int K = g.K, nt = K / BK;
;     unsigned voffA[2], voffB[2];
; #pragma unroll
;     for (int i = 0; i < 2; ++i) { int R, C; stage_rc(tid * 16 + i * 8192, R, C); const int Rb = Epi::PERM ? ((R & ~31) + perm32(R & 31)) : R;
;         voffA[i] = (unsigned)(R * g.lda + C) * 2u; voffB[i] = (unsigned)(Rb * g.ldb + C) * 2u; }
;     const size_t kstep = (size_t)(BK * 2);
;     const size_t hstepA = (size_t)HALF * g.lda * 2, hstepB = (size_t)HALF * g.ldb * 2;
;     const size_t tstepA = 2 * hstepA, tstepB = 2 * hstepB;
;     const unsigned ldsw = (unsigned)wid * 1024u;
;     const int aoff = lds_byte(wr * 64 + fr, fq * 8), boff = lds_byte(wc * 32 + fr, fq * 8);
;     ...
;     Unit cur, nxt; int ui = 0;
;     if (!S.next(0, cur)) return;
;     f32x4 acc[2][2][4][2];
; #pragma unroll
;     for (int a = 0; a < 2; ++a)
; #pragma unroll
;         for (int b = 0; b < 2; ++b)
; #pragma unroll
;             for (int m = 0; m < 4; ++m)
; #pragma unroll
;                 for (int n = 0; n < 2; ++n) acc[a][b][m][n] = (f32x4){0.f, 0.f, 0.f, 0.f};
;     bf16x8 At[4][2], B0[2][2], B1[2][2];
;     const char* cA = (const char*)g.A + (size_t)cur.pm * tstepA; const char* cB = (const char*)g.Bt + (size_t)cur.pn * tstepB;
;     PG8_STAGE(PG8_SB(0, 0), cB, voffB); PG8_STAGE(PG8_SA(0, 0), cA, voffA); PG8_STAGE(PG8_SB(0, 1), cB + hstepB, voffB); PG8_STAGE(PG8_SA(0, 1), cA + hstepA, voffA);
;     if (wr == 1) PG8_BAR;
;     PG8_WAIT_V(4); PG8_BAR;
;     PG8_STAGE(PG8_SB(1, 0), cB + kstep, voffB); PG8_STAGE(PG8_SA(1, 0), cA + kstep, voffA); PG8_STAGE(PG8_SB(1, 1), cB + hstepB + kstep, voffB);
;     PG8_WAIT_V(6); PG8_BAR;
.LBB0_106:
	s_or_b64 exec, exec, s[2:3]
	s_add_u32 s14, s30, 0x3b000000
	s_addc_u32 s15, s31, 0
	v_mov_b32_e32 v9, v215
	s_waitcnt lgkmcnt(0)
	s_barrier
	s_cmpk_gt_i32 s6, 0x1d7f
	v_readfirstlane_b32 s33, v9
	s_cbranch_scc1 .LBB0_118
	s_nop 1
	s_cmpk_lt_u32 s33, 0x100
	s_cbranch_scc1 .Lp1_prio_done
	s_setprio 1
.Lp1_prio_done:
	v_lshlrev_b32_e32 v0, 4, v9
	v_add_u32_e32 v1, 0x2000, v0
	v_ashrrev_i32_e32 v2, 31, v1
	v_lshrrev_b32_e32 v2, 22, v2
	v_add_u32_e32 v2, v1, v2
	v_ashrrev_i32_e32 v8, 10, v2
	v_mul_i32_i24_e32 v2, 0x400, v8
	v_sub_u32_e32 v1, v1, v2
	v_lshrrev_b32_e32 v2, 4, v1
	v_bitop3_b32 v1, v2, v1, 32 bitop3:0x6c
	v_ashrrev_i32_e32 v2, 31, v1
	v_lshrrev_b32_e32 v2, 26, v2
	v_add_u32_e32 v2, v1, v2
	v_lshlrev_b32_e32 v3, 3, v8
	v_ashrrev_i32_e32 v10, 6, v2
	v_and_b32_e32 v3, -16, v3
	v_add_u32_e32 v3, v10, v3
	v_and_b32_e32 v4, 3, v10
	s_mov_b32 s0, 0xfffe0
	v_lshrrev_b32_e32 v5, 2, v3
	v_lshlrev_b32_e32 v6, 1, v3
	v_and_b32_e32 v2, 0xc0, v2
	v_and_or_b32 v4, v3, s0, v4
	v_and_b32_e32 v5, 4, v5
	v_and_b32_e32 v6, 24, v6
	v_sub_u32_e32 v1, v1, v2
	v_mov_b32_e32 v2, 1
	v_or3_b32 v4, v4, v5, v6
	v_lshlrev_b32_e32 v5, 5, v8
	v_ashrrev_i16_sdwa v1, v2, sext(v1) dst_sel:DWORD dst_unused:UNUSED_PAD src0_sel:DWORD src1_sel:BYTE_0
	v_and_b32_e32 v5, 32, v5
	v_bfe_i32 v11, v1, 0, 16
	v_add_lshl_u32 v1, v5, v11, 1
	v_lshl_add_u32 v128, v4, 12, v1
	v_lshl_add_u32 v130, v3, 12, v1
	v_bfe_i32 v1, v9, 27, 1
	v_lshrrev_b32_e32 v1, 22, v1
	v_add_u32_e32 v1, v0, v1
	v_and_b32_e32 v1, 0xfffffc00, v1
	v_sub_u32_e32 v0, v0, v1
	v_lshrrev_b32_e32 v1, 4, v0
	v_bitop3_b32 v1, v1, v0, 32 bitop3:0x6c
	v_ashrrev_i32_e32 v0, 31, v0
	v_lshrrev_b32_e32 v0, 26, v0
	v_add_u32_e32 v0, v1, v0
	v_ashrrev_i32_e32 v12, 6, v0
	v_ashrrev_i32_e32 v0, 31, v9
	v_lshrrev_b32_e32 v0, 26, v0
	v_add_u32_e32 v0, v9, v0
	v_ashrrev_i32_e32 v13, 6, v0
	v_lshlrev_b32_e32 v0, 3, v13
	v_and_b32_e32 v0, -16, v0
	v_add_u32_e32 v0, v12, v0
	v_and_b32_e32 v3, 3, v12
	s_ashr_i32 s59, s6, 31
	v_and_or_b32 v3, v0, s0, v3
	s_lshr_b32 s0, s59, 29
	s_add_i32 s0, s6, s0
	s_ashr_i32 s4, s33, 6
	s_ashr_i32 s1, s0, 3
	s_and_b32 s0, s0, -8
	s_ashr_i32 s3, s33, 8
	s_lshl_b32 s58, s4, 10
	s_sub_i32 s0, s6, s0
	s_cmp_lt_i32 s0, 0
	s_movk_i32 s60, 0x3b1
	s_cselect_b32 s2, s60, 0x3b0
	s_mul_i32 s0, s2, s0
	s_add_i32 s0, s0, s1
	s_mul_hi_i32 s1, s0, 0x22b63cbf
	s_lshr_b32 s2, s1, 31
	s_ashr_i32 s1, s1, 6
	s_add_i32 s1, s1, s2
	s_lshl_b32 s5, s1, 3
	s_mulk_i32 s1, 0x1d8
	s_sub_i32 s0, s0, s1
	s_sext_i32_i16 s1, s0
	s_bfe_u32 s1, s1, 0x3001c
	s_add_i32 s1, s0, s1
	s_sext_i32_i16 s2, s1
	s_and_b32 s1, s1, 0xfff8
	v_lshrrev_b32_e32 v4, 2, v0
	v_lshlrev_b32_e32 v5, 1, v0
	s_sub_i32 s0, s0, s1
	v_and_b32_e32 v4, 4, v4
	v_and_b32_e32 v5, 24, v5
	s_sext_i32_i16 s0, s0
	v_or3_b32 v3, v3, v4, v5
	v_mul_i32_i24_e32 v5, 64, v12
	s_lshr_b32 s2, s2, 3
	s_add_i32 s8, s5, s0
	v_sub_u32_e32 v1, v1, v5
	s_ashr_i32 s9, s8, 31
	s_bfe_i64 s[16:17], s[2:3], 0x100000
	v_lshlrev_b32_e32 v4, 5, v13
	v_ashrrev_i16_sdwa v1, v2, sext(v1) dst_sel:DWORD dst_unused:UNUSED_PAD src0_sel:DWORD src1_sel:BYTE_0
	s_lshl_b64 s[0:1], s[8:9], 20
	s_lshl_b64 s[16:17], s[16:17], 20
	v_and_b32_e32 v4, 32, v4
	v_bfe_i32 v14, v1, 0, 16
	s_add_u32 s54, s14, s16
	v_add_lshl_u32 v1, v4, v14, 1
	s_addc_u32 s55, s15, s17
	s_add_i32 s9, s58, 0
	v_lshl_add_u32 v132, v3, 12, v1
	s_add_i32 m0, s9, 0x10000
	v_lshl_add_u32 v134, v0, 12, v1
	global_load_lds_dwordx4 v132, s[54:55]
	s_add_i32 m0, s9, 0x12000
	s_add_u32 s52, s28, s0
	global_load_lds_dwordx4 v128, s[54:55]
	s_addc_u32 s53, s29, s1
	s_mov_b32 m0, s9
	s_add_i32 s61, s9, 0x2000
	global_load_lds_dwordx4 v134, s[52:53]
	s_mov_b32 m0, s61
	s_add_u32 s0, s54, 0x80000
	global_load_lds_dwordx4 v130, s[52:53]
	s_addc_u32 s1, s55, 0
	s_add_i32 m0, s9, 0x14000
	v_mov_b32_e32 v133, 0
	global_load_lds_dwordx4 v132, s[0:1]
	s_add_i32 m0, s9, 0x16000
	v_mov_b32_e32 v129, v133
	global_load_lds_dwordx4 v128, s[0:1]
	s_add_u32 s0, s52, 0x80000
	s_addc_u32 s1, s53, 0
	s_add_i32 s68, s9, 0x4000
	s_mov_b32 m0, s68
	s_add_i32 s69, s9, 0x6000
	global_load_lds_dwordx4 v134, s[0:1]
	s_mov_b32 m0, s69
	v_mov_b32_e32 v135, v133
	global_load_lds_dwordx4 v130, s[0:1]
	v_mov_b32_e32 v131, v133
	s_mov_b32 s70, 0
	v_lshl_add_u64 v[6:7], s[54:55], 0, v[132:133]
	v_lshl_add_u64 v[4:5], s[54:55], 0, v[128:129]
	v_lshl_add_u64 v[2:3], s[52:53], 0, v[134:135]
	s_cmp_lg_u32 s3, 1
	v_lshl_add_u64 v[0:1], s[52:53], 0, v[130:131]
	s_cbranch_scc1 .LBB0_109
	s_barrier

; #define PG8_STAGE(bufoff, gbase, voff) do { _Pragma("unroll") for (int _i = 0; _i < 2; ++_i) \
;         __builtin_amdgcn_global_load_lds((const unsigned*)((const char*)(gbase) + (voff)[_i]), (LAS unsigned*)(lds + (bufoff) + ldsw + _i * 8192), 16, 0, 0); } while (0)
; #define PG8_LDA(dst, b, h) do { _Pragma("unroll") for (int m = 0; m < 4; ++m) _Pragma("unroll") for (int k = 0; k < 2; ++k) dst[m][k] = *(const LAS bf16x8*)(lds + PG8_SA(b, h) + aoff + m * 2048 + k * 1024); } while (0)
; #define PG8_LDB(dst, b, h) do { _Pragma("unroll") for (int n = 0; n < 2; ++n) _Pragma("unroll") for (int k = 0; k < 2; ++k) dst[n][k] = *(const LAS bf16x8*)(lds + PG8_SB(b, h) + boff + n * 2048 + k * 1024); } while (0)
; #define PG8_MMA(ai, bj, At, Bt) do { __builtin_amdgcn_s_setprio(1); _Pragma("unroll") for (int m = 0; m < 4; ++m) _Pragma("unroll") for (int n = 0; n < 2; ++n) _Pragma("unroll") for (int k = 0; k < 2; ++k) \
;         acc[ai][bj][m][n] = __builtin_amdgcn_mfma_f32_16x16x32_bf16(Bt[n][k], At[m][k], acc[ai][bj][m][n], 0, 0, 0); __builtin_amdgcn_s_setprio(0); } while (0)
; #define PG8_WAIT_V(n) asm volatile("s_waitcnt vmcnt(" #n ")" ::: "memory")
; #define PG8_WAIT_L(n) asm volatile("s_waitcnt lgkmcnt(" #n ")" ::: "memory")
; #define PG8_BAR __builtin_amdgcn_s_barrier()
; #define PG8_SCHED __builtin_amdgcn_sched_barrier(0)
; template <class Epi>
; DI void gemm_phase(LAS unsigned char* lds, const Gemm g, const StaticOrder& S, const Epi& E) {
;     ...
;             PG8_LDB(B0, 0, 0); PG8_SCHED; PG8_LDA(At, 0, 0); PG8_STAGE(PG8_SA(1, 1), a1 + hstepA, voffA);
;             PG8_WAIT_L(8); PG8_BAR; PG8_WAIT_L(0); PG8_MMA(0, 0, At, B0); PG8_BAR; PG8_SCHED;
;             PG8_LDB(B1, 0, 1); PG8_STAGE(PG8_SB(0, 0), b2, voffB);
;             PG8_BAR; PG8_WAIT_L(0); PG8_MMA(0, 1, At, B1); PG8_BAR;
;             PG8_LDA(At, 0, 1); PG8_STAGE(PG8_SA(0, 0), a2, voffA);
;             PG8_BAR; PG8_WAIT_L(0); PG8_MMA(1, 0, At, B0); PG8_BAR; PG8_SCHED;
;             PG8_STAGE(PG8_SB(0, 1), b2 + hstepB, voffB);
;             PG8_WAIT_V(6); PG8_BAR; PG8_MMA(1, 1, At, B1); PG8_BAR;
.LBB0_113:
	ds_read_b128 v[150:153], v147
	ds_read_b128 v[154:157], v147 offset:1024
	ds_read_b128 v[158:161], v147 offset:2048
	ds_read_b128 v[162:165], v147 offset:3072
	s_add_u32 s0, s52, 0xfff80080
	s_addc_u32 s1, s53, -1
	s_cmp_eq_u32 s83, 28
	s_cselect_b32 s57, s47, s1
	s_cselect_b32 s56, s79, s0
	s_cselect_b32 s55, s17, s82
	s_cselect_b32 s54, s80, s81
	v_lshl_add_u64 v[170:171], s[52:53], 0, v[136:137]
	s_add_i32 m0, s9, 0xc000
	ds_read_b128 v[166:169], v148
	ds_read_b128 v[174:177], v148 offset:1024
	ds_read_b128 v[178:181], v148 offset:2048
	ds_read_b128 v[182:185], v148 offset:3072
	ds_read_b128 v[186:189], v148 offset:4096
	ds_read_b128 v[190:193], v148 offset:5120
	ds_read_b128 v[194:197], v148 offset:6144
	ds_read_b128 v[198:201], v148 offset:7168
	global_load_lds_dwordx4 v[170:171], off
	v_lshl_add_u64 v[170:171], s[52:53], 0, v[138:139]
	s_add_i32 m0, s9, 0xe000
	s_nop 0
	global_load_lds_dwordx4 v[170:171], off
	s_waitcnt lgkmcnt(8)
	s_barrier
	s_waitcnt lgkmcnt(0)
	s_waitcnt lgkmcnt(0)
	v_mfma_f32_16x16x32_bf16 v[124:127], v[150:153], v[166:169], v[124:127]
	v_mfma_f32_16x16x32_bf16 v[120:123], v[158:161], v[166:169], v[120:123]
	v_mfma_f32_16x16x32_bf16 v[116:119], v[150:153], v[178:181], v[116:119]
	v_mfma_f32_16x16x32_bf16 v[112:115], v[158:161], v[178:181], v[112:115]
	v_mfma_f32_16x16x32_bf16 v[100:103], v[150:153], v[186:189], v[100:103]
	v_mfma_f32_16x16x32_bf16 v[96:99], v[158:161], v[186:189], v[96:99]
	v_mfma_f32_16x16x32_bf16 v[84:87], v[150:153], v[194:197], v[84:87]
	v_mfma_f32_16x16x32_bf16 v[80:83], v[158:161], v[194:197], v[80:83]
	v_mfma_f32_16x16x32_bf16 v[124:127], v[154:157], v[174:177], v[124:127]
	v_mfma_f32_16x16x32_bf16 v[120:123], v[162:165], v[174:177], v[120:123]
	v_mfma_f32_16x16x32_bf16 v[116:119], v[154:157], v[182:185], v[116:119]
	v_mfma_f32_16x16x32_bf16 v[112:115], v[162:165], v[182:185], v[112:115]
	v_mfma_f32_16x16x32_bf16 v[100:103], v[154:157], v[190:193], v[100:103]
	v_mfma_f32_16x16x32_bf16 v[96:99], v[162:165], v[190:193], v[96:99]
	v_mfma_f32_16x16x32_bf16 v[84:87], v[154:157], v[198:201], v[84:87]
	v_mfma_f32_16x16x32_bf16 v[80:83], v[162:165], v[198:201], v[80:83]
	s_barrier
	s_add_i32 s0, s75, s58
	v_lshl_add_u64 v[170:171], s[54:55], 0, v[132:133]
	s_mov_b32 m0, s0
	ds_read_b128 v[202:205], v149
	ds_read_b128 v[206:209], v149 offset:1024
	ds_read_b128 v[210:213], v149 offset:2048
	ds_read_b128 v[216:219], v149 offset:3072
	global_load_lds_dwordx4 v[170:171], off
	v_lshl_add_u64 v[220:221], s[54:55], 0, v[128:129]
	s_add_i32 m0, s0, 0x2000
	s_nop 0
	global_load_lds_dwordx4 v[220:221], off
	s_barrier
	s_waitcnt lgkmcnt(0)
	s_waitcnt lgkmcnt(0)
	v_mfma_f32_16x16x32_bf16 v[108:111], v[202:205], v[166:169], v[108:111]
	v_mfma_f32_16x16x32_bf16 v[104:107], v[210:213], v[166:169], v[104:107]
	v_mfma_f32_16x16x32_bf16 v[92:95], v[202:205], v[178:181], v[92:95]
	v_mfma_f32_16x16x32_bf16 v[88:91], v[210:213], v[178:181], v[88:91]
	v_mfma_f32_16x16x32_bf16 v[76:79], v[202:205], v[186:189], v[76:79]
	v_mfma_f32_16x16x32_bf16 v[72:75], v[210:213], v[186:189], v[72:75]
	v_mfma_f32_16x16x32_bf16 v[68:71], v[202:205], v[194:197], v[68:71]
	v_mfma_f32_16x16x32_bf16 v[64:67], v[210:213], v[194:197], v[64:67]
	v_mfma_f32_16x16x32_bf16 v[108:111], v[206:209], v[174:177], v[108:111]
	v_mfma_f32_16x16x32_bf16 v[104:107], v[216:219], v[174:177], v[104:107]
	v_mfma_f32_16x16x32_bf16 v[92:95], v[206:209], v[182:185], v[92:95]
	v_mfma_f32_16x16x32_bf16 v[88:91], v[216:219], v[182:185], v[88:91]
	v_mfma_f32_16x16x32_bf16 v[76:79], v[206:209], v[190:193], v[76:79]
	v_mfma_f32_16x16x32_bf16 v[72:75], v[216:219], v[190:193], v[72:75]
	v_mfma_f32_16x16x32_bf16 v[68:71], v[206:209], v[198:201], v[68:71]
	v_mfma_f32_16x16x32_bf16 v[64:67], v[216:219], v[198:201], v[64:67]
	s_mov_b32 m0, s9
	v_lshl_add_u64 v[222:223], s[56:57], 0, v[134:135]
	s_barrier
	ds_read_b128 v[166:169], v148 offset:16384
	ds_read_b128 v[174:177], v148 offset:17408
	ds_read_b128 v[178:181], v148 offset:18432
	ds_read_b128 v[182:185], v148 offset:19456
	ds_read_b128 v[186:189], v148 offset:20480
	ds_read_b128 v[190:193], v148 offset:21504
	ds_read_b128 v[194:197], v148 offset:22528
	ds_read_b128 v[198:201], v148 offset:23552
	global_load_lds_dwordx4 v[222:223], off
	v_lshl_add_u64 v[224:225], s[56:57], 0, v[130:131]
	s_mov_b32 m0, s61
	s_nop 0
	global_load_lds_dwordx4 v[224:225], off
	s_barrier
	s_waitcnt lgkmcnt(0)
	s_waitcnt lgkmcnt(0)
	v_mfma_f32_16x16x32_bf16 v[60:63], v[150:153], v[166:169], v[60:63]
	v_mfma_f32_16x16x32_bf16 v[56:59], v[158:161], v[166:169], v[56:59]
	v_mfma_f32_16x16x32_bf16 v[52:55], v[150:153], v[178:181], v[52:55]
	v_mfma_f32_16x16x32_bf16 v[48:51], v[158:161], v[178:181], v[48:51]
	v_mfma_f32_16x16x32_bf16 v[36:39], v[150:153], v[186:189], v[36:39]
	v_mfma_f32_16x16x32_bf16 v[32:35], v[158:161], v[186:189], v[32:35]
	v_mfma_f32_16x16x32_bf16 v[20:23], v[150:153], v[194:197], v[20:23]
	v_mfma_f32_16x16x32_bf16 v[16:19], v[158:161], v[194:197], v[16:19]
	v_mfma_f32_16x16x32_bf16 v[60:63], v[154:157], v[174:177], v[60:63]
	v_mfma_f32_16x16x32_bf16 v[56:59], v[162:165], v[174:177], v[56:59]
	v_mfma_f32_16x16x32_bf16 v[52:55], v[154:157], v[182:185], v[52:55]
	v_mfma_f32_16x16x32_bf16 v[48:51], v[162:165], v[182:185], v[48:51]
	v_mfma_f32_16x16x32_bf16 v[36:39], v[154:157], v[190:193], v[36:39]
	v_mfma_f32_16x16x32_bf16 v[32:35], v[162:165], v[190:193], v[32:35]
	v_mfma_f32_16x16x32_bf16 v[20:23], v[154:157], v[198:201], v[20:23]
	v_mfma_f32_16x16x32_bf16 v[16:19], v[162:165], v[198:201], v[16:19]
	s_barrier
; #define PG8_STAGE(bufoff, gbase, voff) do { _Pragma("unroll") for (int _i = 0; _i < 2; ++_i) \
;         __builtin_amdgcn_global_load_lds((const unsigned*)((const char*)(gbase) + (voff)[_i]), (LAS unsigned*)(lds + (bufoff) + ldsw + _i * 8192), 16, 0, 0); } while (0)
; #define PG8_LDA(dst, b, h) do { _Pragma("unroll") for (int m = 0; m < 4; ++m) _Pragma("unroll") for (int k = 0; k < 2; ++k) dst[m][k] = *(const LAS bf16x8*)(lds + PG8_SA(b, h) + aoff + m * 2048 + k * 1024); } while (0)
; #define PG8_LDB(dst, b, h) do { _Pragma("unroll") for (int n = 0; n < 2; ++n) _Pragma("unroll") for (int k = 0; k < 2; ++k) dst[n][k] = *(const LAS bf16x8*)(lds + PG8_SB(b, h) + boff + n * 2048 + k * 1024); } while (0)
; #define PG8_MMA(ai, bj, At, Bt) do { __builtin_amdgcn_s_setprio(1); _Pragma("unroll") for (int m = 0; m < 4; ++m) _Pragma("unroll") for (int n = 0; n < 2; ++n) _Pragma("unroll") for (int k = 0; k < 2; ++k) \
;         acc[ai][bj][m][n] = __builtin_amdgcn_mfma_f32_16x16x32_bf16(Bt[n][k], At[m][k], acc[ai][bj][m][n], 0, 0, 0); __builtin_amdgcn_s_setprio(0); } while (0)
; #define PG8_WAIT_V(n) asm volatile("s_waitcnt vmcnt(" #n ")" ::: "memory")
; #define PG8_WAIT_L(n) asm volatile("s_waitcnt lgkmcnt(" #n ")" ::: "memory")
; #define PG8_BAR __builtin_amdgcn_s_barrier()
; #define PG8_SCHED __builtin_amdgcn_sched_barrier(0)
; template <class Epi>
; DI void gemm_phase(LAS unsigned char* lds, const Gemm g, const StaticOrder& S, const Epi& E) {
;     ...
;             PG8_WAIT_V(6); PG8_BAR; PG8_MMA(1, 1, At, B1); PG8_BAR;
;             PG8_LDB(B0, 1, 0); PG8_SCHED; PG8_LDA(At, 1, 0); PG8_STAGE(PG8_SA(0, 1), a2 + hstepA, voffA);
;             PG8_WAIT_L(8); PG8_BAR; PG8_WAIT_L(0); PG8_MMA(0, 0, At, B0); PG8_BAR; PG8_SCHED;
;             PG8_LDB(B1, 1, 1); PG8_STAGE(PG8_SB(1, 0), b3, voffB);
;             PG8_BAR; PG8_WAIT_L(0); PG8_MMA(0, 1, At, B1); PG8_BAR;
;             PG8_LDA(At, 1, 1); PG8_STAGE(PG8_SA(1, 0), a3, voffA);
;             PG8_BAR; PG8_WAIT_L(0); PG8_MMA(1, 0, At, B0); PG8_BAR; PG8_SCHED;
	s_add_u32 s0, s54, 0x80000
	s_addc_u32 s1, s55, 0
	s_add_i32 s84, s76, s58
	v_lshl_add_u64 v[150:151], s[0:1], 0, v[132:133]
	s_mov_b32 m0, s84
	s_nop 0
	global_load_lds_dwordx4 v[150:151], off
	v_lshl_add_u64 v[150:151], s[0:1], 0, v[128:129]
	s_add_i32 m0, s84, 0x2000
	s_nop 0
	global_load_lds_dwordx4 v[150:151], off
	s_waitcnt vmcnt(6)
	s_barrier
	v_mfma_f32_16x16x32_bf16 v[44:47], v[202:205], v[166:169], v[44:47]
	v_mfma_f32_16x16x32_bf16 v[40:43], v[210:213], v[166:169], v[40:43]
	v_mfma_f32_16x16x32_bf16 v[28:31], v[202:205], v[178:181], v[28:31]
	v_mfma_f32_16x16x32_bf16 v[24:27], v[210:213], v[178:181], v[24:27]
	v_mfma_f32_16x16x32_bf16 v[12:15], v[202:205], v[186:189], v[12:15]
	v_mfma_f32_16x16x32_bf16 v[8:11], v[210:213], v[186:189], v[8:11]
	v_mfma_f32_16x16x32_bf16 v[4:7], v[202:205], v[194:197], v[4:7]
	v_mfma_f32_16x16x32_bf16 v[0:3], v[210:213], v[194:197], v[0:3]
	v_mfma_f32_16x16x32_bf16 v[44:47], v[206:209], v[174:177], v[44:47]
	v_mfma_f32_16x16x32_bf16 v[40:43], v[216:219], v[174:177], v[40:43]
	v_mfma_f32_16x16x32_bf16 v[28:31], v[206:209], v[182:185], v[28:31]
	v_mfma_f32_16x16x32_bf16 v[24:27], v[216:219], v[182:185], v[24:27]
	v_mfma_f32_16x16x32_bf16 v[12:15], v[206:209], v[190:193], v[12:15]
	v_mfma_f32_16x16x32_bf16 v[8:11], v[216:219], v[190:193], v[8:11]
	v_mfma_f32_16x16x32_bf16 v[4:7], v[206:209], v[198:201], v[4:7]
	v_mfma_f32_16x16x32_bf16 v[0:3], v[216:219], v[198:201], v[0:3]
	s_add_i32 s84, 0, 0x18000
	v_add_u32_e32 v162, s84, v145
	s_barrier
	ds_read_b128 v[150:153], v162
	ds_read_b128 v[154:157], v162 offset:1024
	ds_read_b128 v[158:161], v162 offset:2048
	ds_read_b128 v[162:165], v162 offset:3072
	s_add_u32 s0, s56, 0x80000
	s_addc_u32 s1, s57, 0
	s_mov_b32 m0, s68
	v_lshl_add_u64 v[202:203], s[0:1], 0, v[134:135]
	ds_read_b128 v[166:169], v148 offset:32768
	ds_read_b128 v[174:177], v148 offset:33792
	ds_read_b128 v[178:181], v148 offset:34816
	ds_read_b128 v[182:185], v148 offset:35840
	ds_read_b128 v[186:189], v148 offset:36864
	ds_read_b128 v[190:193], v148 offset:37888
	ds_read_b128 v[194:197], v148 offset:38912
	ds_read_b128 v[198:201], v148 offset:39936
	global_load_lds_dwordx4 v[202:203], off
	v_lshl_add_u64 v[202:203], s[0:1], 0, v[130:131]
	s_mov_b32 m0, s69
	s_nop 0
	global_load_lds_dwordx4 v[202:203], off
	s_waitcnt lgkmcnt(8)
	s_barrier
	s_waitcnt lgkmcnt(0)
	s_waitcnt lgkmcnt(0)
	v_mfma_f32_16x16x32_bf16 v[124:127], v[150:153], v[166:169], v[124:127]
	v_mfma_f32_16x16x32_bf16 v[120:123], v[158:161], v[166:169], v[120:123]
	v_mfma_f32_16x16x32_bf16 v[116:119], v[150:153], v[178:181], v[116:119]
	v_mfma_f32_16x16x32_bf16 v[112:115], v[158:161], v[178:181], v[112:115]
	v_mfma_f32_16x16x32_bf16 v[100:103], v[150:153], v[186:189], v[100:103]
	v_mfma_f32_16x16x32_bf16 v[96:99], v[158:161], v[186:189], v[96:99]
	v_mfma_f32_16x16x32_bf16 v[84:87], v[150:153], v[194:197], v[84:87]
	v_mfma_f32_16x16x32_bf16 v[80:83], v[158:161], v[194:197], v[80:83]
	v_mfma_f32_16x16x32_bf16 v[124:127], v[154:157], v[174:177], v[124:127]
	v_mfma_f32_16x16x32_bf16 v[120:123], v[162:165], v[174:177], v[120:123]
	v_mfma_f32_16x16x32_bf16 v[116:119], v[154:157], v[182:185], v[116:119]
	v_mfma_f32_16x16x32_bf16 v[112:115], v[162:165], v[182:185], v[112:115]
	v_mfma_f32_16x16x32_bf16 v[100:103], v[154:157], v[190:193], v[100:103]
	v_mfma_f32_16x16x32_bf16 v[96:99], v[162:165], v[190:193], v[96:99]
	v_mfma_f32_16x16x32_bf16 v[84:87], v[154:157], v[198:201], v[84:87]
	v_mfma_f32_16x16x32_bf16 v[80:83], v[162:165], v[198:201], v[80:83]
	s_barrier
	s_add_i32 s56, 0, 0x1c000
	s_add_i32 s0, s84, s58
	v_add_u32_e32 v172, s56, v145
	v_lshl_add_u64 v[170:171], v[170:171], 0, s[4:5]
	s_mov_b32 m0, s0
	ds_read_b128 v[202:205], v172
	ds_read_b128 v[206:209], v172 offset:1024
	ds_read_b128 v[210:213], v172 offset:2048
	ds_read_b128 v[216:219], v172 offset:3072
	global_load_lds_dwordx4 v[170:171], off
	v_lshl_add_u64 v[170:171], v[220:221], 0, s[4:5]
	s_add_i32 m0, s0, 0x2000
	s_nop 0
	global_load_lds_dwordx4 v[170:171], off
	s_barrier
	s_waitcnt lgkmcnt(0)
	s_waitcnt lgkmcnt(0)
	v_mfma_f32_16x16x32_bf16 v[108:111], v[202:205], v[166:169], v[108:111]
	v_mfma_f32_16x16x32_bf16 v[104:107], v[210:213], v[166:169], v[104:107]
	v_mfma_f32_16x16x32_bf16 v[92:95], v[202:205], v[178:181], v[92:95]
	v_mfma_f32_16x16x32_bf16 v[88:91], v[210:213], v[178:181], v[88:91]
	v_mfma_f32_16x16x32_bf16 v[76:79], v[202:205], v[186:189], v[76:79]
	v_mfma_f32_16x16x32_bf16 v[72:75], v[210:213], v[186:189], v[72:75]
	v_mfma_f32_16x16x32_bf16 v[68:71], v[202:205], v[194:197], v[68:71]
	v_mfma_f32_16x16x32_bf16 v[64:67], v[210:213], v[194:197], v[64:67]
	v_mfma_f32_16x16x32_bf16 v[108:111], v[206:209], v[174:177], v[108:111]
	v_mfma_f32_16x16x32_bf16 v[104:107], v[216:219], v[174:177], v[104:107]
	v_mfma_f32_16x16x32_bf16 v[92:95], v[206:209], v[182:185], v[92:95]
	v_mfma_f32_16x16x32_bf16 v[88:91], v[216:219], v[182:185], v[88:91]
	v_mfma_f32_16x16x32_bf16 v[76:79], v[206:209], v[190:193], v[76:79]
	v_mfma_f32_16x16x32_bf16 v[72:75], v[216:219], v[190:193], v[72:75]
	v_mfma_f32_16x16x32_bf16 v[68:71], v[206:209], v[198:201], v[68:71]
	v_mfma_f32_16x16x32_bf16 v[64:67], v[216:219], v[198:201], v[64:67]
	s_mov_b32 m0, s71
	v_lshl_add_u64 v[170:171], v[222:223], 0, s[4:5]
	s_barrier
	ds_read_b128 v[166:169], v148 offset:49152
	ds_read_b128 v[174:177], v148 offset:50176
	ds_read_b128 v[178:181], v148 offset:51200
	ds_read_b128 v[182:185], v148 offset:52224
	ds_read_b128 v[186:189], v148 offset:53248
	ds_read_b128 v[190:193], v148 offset:54272
	ds_read_b128 v[194:197], v148 offset:55296
	ds_read_b128 v[198:201], v148 offset:56320
	global_load_lds_dwordx4 v[170:171], off
	v_lshl_add_u64 v[170:171], v[224:225], 0, s[4:5]
	s_mov_b32 m0, s72
	s_nop 0
	global_load_lds_dwordx4 v[170:171], off
	s_barrier
; #define PG8_STAGE(bufoff, gbase, voff) do { _Pragma("unroll") for (int _i = 0; _i < 2; ++_i) \
;         __builtin_amdgcn_global_load_lds((const unsigned*)((const char*)(gbase) + (voff)[_i]), (LAS unsigned*)(lds + (bufoff) + ldsw + _i * 8192), 16, 0, 0); } while (0)
; #define PG8_MMA(ai, bj, At, Bt) do { __builtin_amdgcn_s_setprio(1); _Pragma("unroll") for (int m = 0; m < 4; ++m) _Pragma("unroll") for (int n = 0; n < 2; ++n) _Pragma("unroll") for (int k = 0; k < 2; ++k) \
;         acc[ai][bj][m][n] = __builtin_amdgcn_mfma_f32_16x16x32_bf16(Bt[n][k], At[m][k], acc[ai][bj][m][n], 0, 0, 0); __builtin_amdgcn_s_setprio(0); } while (0)
; #define PG8_WAIT_V(n) asm volatile("s_waitcnt vmcnt(" #n ")" ::: "memory")
; #define PG8_WAIT_L(n) asm volatile("s_waitcnt lgkmcnt(" #n ")" ::: "memory")
; #define PG8_BAR __builtin_amdgcn_s_barrier()
; #define PG8_SCHED __builtin_amdgcn_sched_barrier(0)
; template <class Epi>
; DI void gemm_phase(LAS unsigned char* lds, const Gemm g, const StaticOrder& S, const Epi& E) {
;     ...
;             PG8_BAR; PG8_WAIT_L(0); PG8_MMA(1, 0, At, B0); PG8_BAR; PG8_SCHED;
;             PG8_STAGE(PG8_SB(1, 1), b3 + hstepB, voffB);
;             PG8_WAIT_V(6); PG8_BAR; PG8_MMA(1, 1, At, B1); PG8_BAR;
;         }
;         E(acc, cur, wr, wc, fr, fq);
	s_waitcnt lgkmcnt(0)
	s_waitcnt lgkmcnt(0)
	v_mfma_f32_16x16x32_bf16 v[60:63], v[150:153], v[166:169], v[60:63]
	v_mfma_f32_16x16x32_bf16 v[56:59], v[158:161], v[166:169], v[56:59]
	v_mfma_f32_16x16x32_bf16 v[52:55], v[150:153], v[178:181], v[52:55]
	v_mfma_f32_16x16x32_bf16 v[48:51], v[158:161], v[178:181], v[48:51]
	v_mfma_f32_16x16x32_bf16 v[36:39], v[150:153], v[186:189], v[36:39]
	v_mfma_f32_16x16x32_bf16 v[32:35], v[158:161], v[186:189], v[32:35]
	v_mfma_f32_16x16x32_bf16 v[20:23], v[150:153], v[194:197], v[20:23]
	v_mfma_f32_16x16x32_bf16 v[16:19], v[158:161], v[194:197], v[16:19]
	v_mfma_f32_16x16x32_bf16 v[60:63], v[154:157], v[174:177], v[60:63]
	v_mfma_f32_16x16x32_bf16 v[56:59], v[162:165], v[174:177], v[56:59]
	v_mfma_f32_16x16x32_bf16 v[52:55], v[154:157], v[182:185], v[52:55]
	v_mfma_f32_16x16x32_bf16 v[48:51], v[162:165], v[182:185], v[48:51]
	v_mfma_f32_16x16x32_bf16 v[36:39], v[154:157], v[190:193], v[36:39]
	v_mfma_f32_16x16x32_bf16 v[32:35], v[162:165], v[190:193], v[32:35]
	v_mfma_f32_16x16x32_bf16 v[20:23], v[154:157], v[198:201], v[20:23]
	v_mfma_f32_16x16x32_bf16 v[16:19], v[162:165], v[198:201], v[16:19]
	s_barrier
	s_add_u32 s0, s54, 0x80080
	s_addc_u32 s1, s55, 0
	s_add_i32 s54, s56, s58
	v_lshl_add_u64 v[150:151], s[0:1], 0, v[132:133]
	s_mov_b32 m0, s54
	s_nop 0
	global_load_lds_dwordx4 v[150:151], off
	v_lshl_add_u64 v[150:151], s[0:1], 0, v[128:129]
	s_add_i32 m0, s54, 0x2000
	s_nop 0
	global_load_lds_dwordx4 v[150:151], off
	s_waitcnt vmcnt(6)
	s_barrier
	v_mfma_f32_16x16x32_bf16 v[44:47], v[202:205], v[166:169], v[44:47]
	v_mfma_f32_16x16x32_bf16 v[40:43], v[210:213], v[166:169], v[40:43]
	v_mfma_f32_16x16x32_bf16 v[28:31], v[202:205], v[178:181], v[28:31]
	v_mfma_f32_16x16x32_bf16 v[24:27], v[210:213], v[178:181], v[24:27]
	v_mfma_f32_16x16x32_bf16 v[12:15], v[202:205], v[186:189], v[12:15]
	v_mfma_f32_16x16x32_bf16 v[8:11], v[210:213], v[186:189], v[8:11]
	v_mfma_f32_16x16x32_bf16 v[4:7], v[202:205], v[194:197], v[4:7]
	v_mfma_f32_16x16x32_bf16 v[0:3], v[210:213], v[194:197], v[0:3]
	v_mfma_f32_16x16x32_bf16 v[44:47], v[206:209], v[174:177], v[44:47]
	v_mfma_f32_16x16x32_bf16 v[40:43], v[216:219], v[174:177], v[40:43]
	v_mfma_f32_16x16x32_bf16 v[28:31], v[206:209], v[182:185], v[28:31]
	v_mfma_f32_16x16x32_bf16 v[24:27], v[216:219], v[182:185], v[24:27]
	v_mfma_f32_16x16x32_bf16 v[12:15], v[206:209], v[190:193], v[12:15]
	v_mfma_f32_16x16x32_bf16 v[8:11], v[216:219], v[190:193], v[8:11]
	v_mfma_f32_16x16x32_bf16 v[4:7], v[206:209], v[198:201], v[4:7]
	v_mfma_f32_16x16x32_bf16 v[0:3], v[216:219], v[198:201], v[0:3]
	s_add_i32 s83, s83, 2
	s_add_u32 s52, s52, 0x100
	s_addc_u32 s53, s53, 0
	s_add_u32 s81, s81, 0x100
	s_addc_u32 s82, s82, 0
	s_cmp_gt_u32 s83, 29
	s_barrier
	s_cbranch_scc0 .LBB0_113
; DI unsigned pk2(float lo, float hi) { f32x2 v = {lo, hi}; bf16x2_t b = __builtin_convertvector(v, bf16x2_t); return __builtin_bit_cast(unsigned, b); }
; #define PG8_WAIT_V(n) asm volatile("s_waitcnt vmcnt(" #n ")" ::: "memory")
; #define PG8_BAR __builtin_amdgcn_s_barrier()
; template <class Epi>
; DI void gemm_phase(LAS unsigned char* lds, const Gemm g, const StaticOrder& S, const Epi& E) {
;     ...
;         E(acc, cur, wr, wc, fr, fq);
;         if (!has_next) break;
; #pragma unroll
;         for (int a = 0; a < 2; ++a)
; #pragma unroll
;             for (int b = 0; b < 2; ++b)
; #pragma unroll
;                 for (int m = 0; m < 4; ++m)
; #pragma unroll
;                     for (int n = 0; n < 2; ++n) acc[a][b][m][n] = (f32x4){0.f, 0.f, 0.f, 0.f};
;         cur = nxt; cA = nA; cB = nB; ++ui;
;     }
;     PG8_WAIT_V(0);
;     if (wr == 0) PG8_BAR;
;     PG8_BAR;
;     DI void operator()(const f32x4 (&acc)[2][2][4][2], const Unit& u, int wr, int wc, int fr, int fq) const {
;         const int row0 = u.pm * BM + wr * 64 + fr, col0 = u.pn * BM + wc * 32 + 8 * fq;
; #pragma unroll
;         for (int ai = 0; ai < 2; ++ai)
; #pragma unroll
;             for (int m = 0; m < 4; ++m) { bf16_t* rowp = O + (size_t)(row0 + ai * HALF + m * 16) * ldc + col0;
; #pragma unroll
;                 for (int bj = 0; bj < 2; ++bj) { const f32x4 v0 = acc[ai][bj][m][0], v1 = acc[ai][bj][m][1];
;                     u32x4 w; w.x = pk2(v0[0], v0[1]); w.y = pk2(v0[2], v0[3]); w.z = pk2(v1[0], v1[1]); w.w = pk2(v1[2], v1[3]);
;                     *(u32x4*)(rowp + bj * HALF) = w; } }
	v_lshl_add_u32 v156, s8, 8, v144
	v_lshl_or_b32 v150, s78, 8, v146
	v_ashrrev_i32_e32 v151, 31, v150
	v_mov_b64_e32 v[152:153], s[30:31]
	v_cvt_pk_bf16_f32 v68, v68, v69
	v_cvt_pk_bf16_f32 v69, v70, v71
	v_cvt_pk_bf16_f32 v70, v64, v65
	v_add_u32_e32 v64, 0x80, v156
	v_mad_i64_i32 v[154:155], s[0:1], v156, s77, v[152:153]
	v_lshlrev_b64 v[150:151], 1, v[150:151]
	v_cvt_pk_bf16_f32 v108, v108, v109
	v_cvt_pk_bf16_f32 v109, v110, v111
	v_cvt_pk_bf16_f32 v110, v104, v105
	v_or_b32_e32 v104, 16, v156
	v_mad_i64_i32 v[64:65], s[0:1], v64, s77, v[152:153]
	v_cvt_pk_bf16_f32 v44, v44, v45
	v_cvt_pk_bf16_f32 v45, v46, v47
	v_cvt_pk_bf16_f32 v46, v40, v41
	v_add_u32_e32 v40, 0x90, v156
	v_lshl_add_u64 v[154:155], v[154:155], 0, v[150:151]
	v_cvt_pk_bf16_f32 v111, v106, v107
	v_mad_i64_i32 v[104:105], s[0:1], v104, s77, v[152:153]
	v_cvt_pk_bf16_f32 v92, v92, v93
	v_cvt_pk_bf16_f32 v93, v94, v95
	v_cvt_pk_bf16_f32 v94, v88, v89
	v_or_b32_e32 v88, 32, v156
	v_lshl_add_u64 v[64:65], v[64:65], 0, v[150:151]
	v_cvt_pk_bf16_f32 v47, v42, v43
	v_mad_i64_i32 v[40:41], s[0:1], v40, s77, v[152:153]
	v_cvt_pk_bf16_f32 v28, v28, v29
	v_cvt_pk_bf16_f32 v29, v30, v31
	v_cvt_pk_bf16_f32 v30, v24, v25
	v_add_u32_e32 v24, 0xa0, v156
	global_store_dwordx4 v[154:155], v[108:111], off offset:256 nt
	v_cvt_pk_bf16_f32 v95, v90, v91
	v_mad_i64_i32 v[88:89], s[0:1], v88, s77, v[152:153]
	v_lshl_add_u64 v[108:109], v[104:105], 0, v[150:151]
	v_cvt_pk_bf16_f32 v76, v76, v77
	v_cvt_pk_bf16_f32 v77, v78, v79
	v_cvt_pk_bf16_f32 v78, v72, v73
	v_or_b32_e32 v72, 48, v156
	global_store_dwordx4 v[64:65], v[44:47], off offset:256 nt
	v_cvt_pk_bf16_f32 v31, v26, v27
	v_mad_i64_i32 v[24:25], s[0:1], v24, s77, v[152:153]
	v_lshl_add_u64 v[44:45], v[40:41], 0, v[150:151]
	v_cvt_pk_bf16_f32 v12, v12, v13
	v_cvt_pk_bf16_f32 v13, v14, v15
	v_cvt_pk_bf16_f32 v14, v8, v9
	v_add_u32_e32 v8, 0xb0, v156
	global_store_dwordx4 v[108:109], v[92:95], off offset:256 nt
	v_cvt_pk_bf16_f32 v79, v74, v75
	v_mad_i64_i32 v[72:73], s[0:1], v72, s77, v[152:153]
	v_lshl_add_u64 v[92:93], v[88:89], 0, v[150:151]
	global_store_dwordx4 v[44:45], v[28:31], off offset:256 nt
	v_cvt_pk_bf16_f32 v15, v10, v11
	v_mad_i64_i32 v[8:9], s[0:1], v8, s77, v[152:153]
	v_lshl_add_u64 v[28:29], v[24:25], 0, v[150:151]
	v_cvt_pk_bf16_f32 v124, v124, v125
	v_cvt_pk_bf16_f32 v125, v126, v127
	v_cvt_pk_bf16_f32 v126, v120, v121
	v_cvt_pk_bf16_f32 v127, v122, v123
	v_cvt_pk_bf16_f32 v104, v116, v117
	v_cvt_pk_bf16_f32 v105, v118, v119
	v_cvt_pk_bf16_f32 v106, v112, v113
	v_cvt_pk_bf16_f32 v107, v114, v115
	v_cvt_pk_bf16_f32 v88, v100, v101
	v_cvt_pk_bf16_f32 v89, v102, v103
	v_cvt_pk_bf16_f32 v90, v96, v97
	v_cvt_pk_bf16_f32 v91, v98, v99
	global_store_dwordx4 v[92:93], v[76:79], off offset:256 nt
	v_cvt_pk_bf16_f32 v74, v80, v81
	v_cvt_pk_bf16_f32 v75, v82, v83
	v_lshl_add_u64 v[76:77], v[72:73], 0, v[150:151]
	v_cvt_pk_bf16_f32 v72, v84, v85
	v_cvt_pk_bf16_f32 v73, v86, v87
	v_cvt_pk_bf16_f32 v71, v66, v67
	v_cvt_pk_bf16_f32 v60, v60, v61
	v_cvt_pk_bf16_f32 v61, v62, v63
	v_cvt_pk_bf16_f32 v62, v56, v57
	v_cvt_pk_bf16_f32 v63, v58, v59
	v_cvt_pk_bf16_f32 v40, v52, v53
	v_cvt_pk_bf16_f32 v41, v54, v55
	v_cvt_pk_bf16_f32 v42, v48, v49
	v_cvt_pk_bf16_f32 v43, v50, v51
	v_cvt_pk_bf16_f32 v24, v36, v37
	v_cvt_pk_bf16_f32 v25, v38, v39
	v_cvt_pk_bf16_f32 v26, v32, v33
	v_cvt_pk_bf16_f32 v27, v34, v35
	global_store_dwordx4 v[28:29], v[12:15], off offset:256 nt
	v_cvt_pk_bf16_f32 v10, v16, v17
	v_cvt_pk_bf16_f32 v11, v18, v19
	v_lshl_add_u64 v[12:13], v[8:9], 0, v[150:151]
	v_cvt_pk_bf16_f32 v8, v20, v21
	v_cvt_pk_bf16_f32 v9, v22, v23
	v_cvt_pk_bf16_f32 v4, v4, v5
	v_cvt_pk_bf16_f32 v5, v6, v7
	v_cvt_pk_bf16_f32 v6, v0, v1
	v_cvt_pk_bf16_f32 v7, v2, v3
	s_and_b64 vcc, exec, s[2:3]
	s_mov_b32 s78, s16
	s_mov_b32 s8, s46
	s_mov_b64 s[54:55], s[50:51]
	s_mov_b64 s[52:53], s[48:49]
	global_store_dwordx4 v[154:155], v[124:127], off nt
	global_store_dwordx4 v[108:109], v[104:107], off nt
	global_store_dwordx4 v[92:93], v[88:91], off nt
	global_store_dwordx4 v[76:77], v[72:75], off nt
	global_store_dwordx4 v[76:77], v[68:71], off offset:256 nt
	global_store_dwordx4 v[64:65], v[60:63], off nt
	global_store_dwordx4 v[44:45], v[40:43], off nt
	global_store_dwordx4 v[28:29], v[24:27], off nt
	global_store_dwordx4 v[12:13], v[8:11], off nt
	global_store_dwordx4 v[12:13], v[4:7], off offset:256 nt
	s_cbranch_vccz .LBB0_110
	s_waitcnt vmcnt(0)
	s_cmpk_gt_u32 s33, 0xff
	s_cbranch_scc1 .LBB0_117
	s_barrier

; DI unsigned xb_ld(unsigned* p)              { return __hip_atomic_load(p, __ATOMIC_RELAXED, __HIP_MEMORY_SCOPE_AGENT); }
; DI void xcd_barrier_complete(unsigned* bar, unsigned x, unsigned& nloc, unsigned& nx) {
;     const unsigned G = gridDim.x * gridDim.y * gridDim.z;
;     unsigned sum, cnt, mine, sp = 0u;
;     for (;;) {
;         sum = 0u; cnt = 0u; mine = 0u;
; #pragma unroll
;         for (unsigned j = 0; j < 16; ++j) { const unsigned c = xb_ld(&bar[XB_XCNT(j)]); sum += c; cnt += (c > 0u) ? 1u : 0u; mine = (j == x) ? c : mine; }
; DI void xcd_barrier(const XcdBarrier& b) {
;     asm volatile("s_waitcnt vmcnt(0)" ::: "memory");
;     __syncthreads();
;     if (threadIdx.x == 0) {
;         unsigned* bar = b.bar;
;         __builtin_amdgcn_s_waitcnt(0);
;         unsigned nloc = b.st[0], nx = b.st[1];
;         if (nloc == 0u) { xcd_barrier_complete(bar, b.x, nloc, nx); b.st[0] = nloc; b.st[1] = nx; }
.LBB0_118:
	s_setprio 0
	s_waitcnt vmcnt(0)
	s_waitcnt vmcnt(0) lgkmcnt(0)
	s_barrier
	s_mov_b64 s[2:3], exec
	v_readlane_b32 s0, v236, 0
	v_readlane_b32 s1, v236, 1
	s_and_b64 s[0:1], s[2:3], s[0:1]
	s_mov_b64 exec, s[0:1]
	s_cbranch_execz .LBB0_170
	s_add_i32 s0, 0, 0x27ff0
	v_mov_b32_e32 v0, s0
	s_waitcnt vmcnt(0) expcnt(0) lgkmcnt(0)
	ds_read_b32 v2, v0
	s_add_i32 s0, 0, 0x27ff4
	v_mov_b32_e32 v0, s0
	ds_read_b32 v0, v0
	s_waitcnt lgkmcnt(1)
	v_cmp_ne_u32_e32 vcc, 0, v2
	s_cbranch_vccnz .LBB0_134
	s_add_u32 s4, s30, 0x3f732200
	s_addc_u32 s5, s31, 0
	s_add_u32 s8, s30, 0x3f732400
	s_addc_u32 s9, s31, 0
	s_add_u32 s16, s30, 0x3f732500
	s_addc_u32 s17, s31, 0
	s_add_u32 s46, s30, 0x3f732600
	s_addc_u32 s47, s31, 0
	s_add_u32 s48, s30, 0x3f732700
	s_addc_u32 s49, s31, 0
	s_add_u32 s50, s30, 0x3f732800
	s_addc_u32 s51, s31, 0
	s_add_u32 s52, s30, 0x3f732900
	s_addc_u32 s53, s31, 0
	s_add_u32 s54, s30, 0x3f732a00
	s_addc_u32 s55, s31, 0
	s_add_u32 s56, s30, 0x3f732b00
	s_addc_u32 s57, s31, 0
	s_add_u32 s58, s30, 0x3f732c00
	s_addc_u32 s59, s31, 0
	s_add_u32 s60, s30, 0x3f732d00
	s_addc_u32 s61, s31, 0
	s_add_u32 s68, s30, 0x3f732e00
	s_addc_u32 s69, s31, 0
	s_add_u32 s70, s30, 0x3f732f00
	s_addc_u32 s71, s31, 0
	s_add_u32 s72, s30, 0x3f733000
	s_addc_u32 s73, s31, 0
	s_add_u32 s74, s30, 0x3f733100
	s_addc_u32 s75, s31, 0
	s_add_u32 s76, s30, 0x3f733200
	s_addc_u32 s77, s31, 0
	s_mul_i32 s33, s11, s87
	s_add_u32 s78, s30, 0x3f733300
	s_mul_i32 s33, s33, s10
	s_addc_u32 s79, s31, 0
	s_mov_b32 s86, 1
	v_mov_b32_e32 v16, 0
	s_branch .LBB0_122
